# counted vmcnt ladder in out-proj GEMM K-loops (phases 3,8): prefetched K-tile loads stay in flight across the LDS staging writes
# speedup vs baseline: 1.0081x; 1.0081x over previous
;     ...
;     for (int kt2 = 0; kt2 < KT; kt2 += 2) {
; #pragma unroll
;      for (int par = 0; par < 2; ++par) {
;       const int kt = kt2 + par;
;       if (kt + 2 < KT) {
; #pragma unroll
;         for (int i = 0; i < 4; ++i) ra[par][i] = *(const u32x4*)(ap + (size_t)(64 * i) * K + (kt + 2) * BK);
; #pragma unroll
;         for (int i = 0; i < 2; ++i) rb[par][i] = *(const u32x4*)(bp + (size_t)(64 * i) * K + (kt + 2) * BK);
;       }
;       const unsigned char* abase = smem + par * BUFB + (wm * 64 + l15) * LR + g * 16;
;       const unsigned char* bbase = smem + par * BUFB + BM * LR + (wn * 64 + l15) * LR + g * 16;
;       if (!skip_mma)
; #pragma unroll
;       for (int ks = 0; ks < 2; ++ks) {
;         bf16x8 af[4], bfr[2];
; #pragma unroll
;         for (int mf = 0; mf < 4; ++mf) af[mf] = *(const bf16x8*)(abase + mf * 16 * LR + ks * 64);
; #pragma unroll
;         for (int nh = 0; nh < 2; ++nh) {
; #pragma unroll
;           for (int n2 = 0; n2 < 2; ++n2) bfr[n2] = *(const bf16x8*)(bbase + (nh * 2 + n2) * 16 * LR + ks * 64);
; #pragma unroll
;           for (int mf = 0; mf < 4; ++mf)
; #pragma unroll
;             for (int n2 = 0; n2 < 2; ++n2)
;               acc[mf][nh * 2 + n2] = __builtin_amdgcn_mfma_f32_16x16x32_bf16(af[mf], bfr[n2], acc[mf][nh * 2 + n2], 0, 0, 0);
;         }
;       }
;       if (NH > 0) {
;         const int per = KT / NH;
;         if (((kt + 1) % per) == 0) {
;           const int h = (kt + 1) / per - 1;
; #pragma unroll
;           for (int mf = 0; mf < 4; ++mf)
; #pragma unroll
;             for (int r = 0; r < 4; ++r) {
;               float s = rstdS[(wm * 64 + mf * 16 + 4 * g + r) * NH + h];
; #pragma unroll
;               for (int nf = 0; nf < 4; ++nf) {
;                 accT[mf][nf][r] += s * acc[mf][nf][r];
;                 acc[mf][nf][r] = 0.f;
;               }
;             }
;         }
;       }
;       if (kt + 1 < KT) {
;         unsigned char* base = smem + (par ^ 1) * BUFB;
; #pragma unroll
;         for (int i = 0; i < 4; ++i) *(u32x4*)(base + (srow + 64 * i) * LR + skc * 16) = ra[par ^ 1][i];
; #pragma unroll
;         for (int i = 0; i < 2; ++i) *(u32x4*)(base + BM * LR + (srow + 64 * i) * LR + skc * 16) = rb[par ^ 1][i];
;       }
;       __syncthreads();
;      }
.LBB0_715:
	ds_read_b128 v[214:217], v212
	ds_read_b128 v[218:221], v206 offset:36864
	ds_read_b128 v[226:229], v212 offset:2304
	ds_read_b128 v[230:233], v212 offset:4608
	ds_read_b128 v[234:237], v212 offset:6912
	ds_read_b128 v[222:225], v206 offset:39168
	s_waitcnt lgkmcnt(4)
	v_mfma_f32_16x16x32_bf16 v[176:179], v[214:217], v[218:221], v[176:179]
	s_andn2_b64 vcc, exec, s[20:21]
	ds_read_b128 v[250:253], v212 offset:6976
	ds_read_b128 v[246:249], v212 offset:4672
	s_waitcnt lgkmcnt(5)
	v_mfma_f32_16x16x32_bf16 v[160:163], v[226:229], v[218:221], v[160:163]
	s_waitcnt lgkmcnt(4)
	v_mfma_f32_16x16x32_bf16 v[144:147], v[230:233], v[218:221], v[144:147]
	s_waitcnt lgkmcnt(3)
	v_mfma_f32_16x16x32_bf16 v[218:221], v[234:237], v[218:221], v[124:127]
	s_nop 2
	ds_read_b128 v[124:127], v206 offset:43776
	s_waitcnt lgkmcnt(3)
	v_mfma_f32_16x16x32_bf16 v[172:175], v[214:217], v[222:225], v[172:175]
	v_mfma_f32_16x16x32_bf16 v[156:159], v[226:229], v[222:225], v[156:159]
	v_mfma_f32_16x16x32_bf16 v[140:143], v[230:233], v[222:225], v[140:143]
	v_mfma_f32_16x16x32_bf16 v[222:225], v[234:237], v[222:225], v[120:123]
	s_nop 2
	ds_read_b128 v[120:123], v206 offset:41472
	s_waitcnt lgkmcnt(0)
	v_mfma_f32_16x16x32_bf16 v[168:171], v[214:217], v[120:123], v[168:171]
	v_mfma_f32_16x16x32_bf16 v[164:167], v[214:217], v[124:127], v[164:167]
	v_mfma_f32_16x16x32_bf16 v[214:217], v[226:229], v[120:123], v[152:155]
	s_nop 2
	ds_read_b128 v[152:155], v212 offset:64
	v_mfma_f32_16x16x32_bf16 v[226:229], v[226:229], v[124:127], v[148:151]
	s_nop 2
	ds_read_b128 v[148:151], v206 offset:36928
	v_mfma_f32_16x16x32_bf16 v[242:245], v[234:237], v[120:123], v[128:131]
	v_mfma_f32_16x16x32_bf16 v[234:237], v[234:237], v[124:127], v[116:119]
	s_waitcnt lgkmcnt(0)
	v_mfma_f32_16x16x32_bf16 v[116:119], v[152:155], v[148:151], v[176:179]
	s_nop 2
	ds_read_b128 v[176:179], v206 offset:39232
	v_mfma_f32_16x16x32_bf16 v[238:241], v[230:233], v[120:123], v[136:139]
	s_waitcnt lgkmcnt(0)
	v_mfma_f32_16x16x32_bf16 v[120:123], v[152:155], v[176:179], v[172:175]
	s_nop 2
	ds_read_b128 v[172:175], v212 offset:2368
	v_mfma_f32_16x16x32_bf16 v[230:233], v[230:233], v[124:127], v[132:135]
	s_waitcnt lgkmcnt(0)
	v_mfma_f32_16x16x32_bf16 v[128:131], v[172:175], v[176:179], v[156:159]
	v_mfma_f32_16x16x32_bf16 v[132:135], v[246:249], v[148:151], v[144:147]
	v_mfma_f32_16x16x32_bf16 v[136:139], v[246:249], v[176:179], v[140:143]
	v_mfma_f32_16x16x32_bf16 v[140:143], v[250:253], v[148:151], v[218:221]
	v_mfma_f32_16x16x32_bf16 v[144:147], v[250:253], v[176:179], v[222:225]
	ds_read_b128 v[176:179], v206 offset:41536
	s_nop 0
	ds_read_b128 v[218:221], v206 offset:43840
	s_cbranch_vccnz .Lop3_lad_tail
	s_waitcnt vmcnt(11)
	ds_write_b128 v205, v[92:95] offset:55296
	s_waitcnt vmcnt(9)
	ds_write_b128 v205, v[96:99] offset:64512
	v_mfma_f32_16x16x32_bf16 v[124:127], v[172:175], v[148:151], v[160:163]
	s_waitcnt vmcnt(8)
	ds_write_b128 v207, v[100:103] offset:55296
	s_waitcnt vmcnt(7)
	ds_write_b128 v208, v[104:107] offset:55296
	ds_write_b128 v209, v[108:111]
	s_waitcnt vmcnt(6)
	ds_write_b128 v209, v[112:115] offset:9216
.Lop3_lad_join:
	s_waitcnt lgkmcnt(0)
	v_mfma_f32_16x16x32_bf16 v[148:151], v[152:155], v[176:179], v[168:171]
	s_barrier
	v_mfma_f32_16x16x32_bf16 v[152:155], v[152:155], v[218:221], v[164:167]
	v_mfma_f32_16x16x32_bf16 v[156:159], v[172:175], v[176:179], v[214:217]
	v_mfma_f32_16x16x32_bf16 v[160:163], v[172:175], v[218:221], v[226:229]
	v_mfma_f32_16x16x32_bf16 v[168:171], v[246:249], v[176:179], v[238:241]
	v_mfma_f32_16x16x32_bf16 v[172:175], v[246:249], v[218:221], v[230:233]
	v_mfma_f32_16x16x32_bf16 v[176:179], v[250:253], v[176:179], v[242:245]
	v_mfma_f32_16x16x32_bf16 v[164:167], v[250:253], v[218:221], v[234:237]
	s_cbranch_vccnz .LBB0_717
	v_add_co_u32_e32 v92, vcc, 0x11262000, v192
	s_nop 1
	v_addc_co_u32_e32 v93, vcc, 0, v193, vcc
	v_add_co_u32_e32 v96, vcc, 0x112a2000, v192
	s_nop 1
	v_addc_co_u32_e32 v97, vcc, 0, v193, vcc
	v_add_co_u32_e32 v100, vcc, 0x112e2000, v192
	global_load_dwordx4 v[92:95], v[92:93], off offset:384
	s_nop 0
	global_load_dwordx4 v[96:99], v[96:97], off offset:384
	v_addc_co_u32_e32 v101, vcc, 0, v193, vcc
	v_add_co_u32_e32 v104, vcc, 0x11322000, v192
	s_nop 1
	v_addc_co_u32_e32 v105, vcc, 0, v193, vcc
	v_add_co_u32_e32 v108, vcc, 0xc00000, v190
	global_load_dwordx4 v[100:103], v[100:101], off offset:384
	s_nop 0
	global_load_dwordx4 v[104:107], v[104:105], off offset:384
	v_addc_co_u32_e32 v109, vcc, 0, v191, vcc
	v_add_co_u32_e32 v112, vcc, 0xc40000, v190
	s_nop 1
	v_addc_co_u32_e32 v113, vcc, 0, v191, vcc
	global_load_dwordx4 v[108:111], v[108:109], off offset:384
	s_nop 0
	global_load_dwordx4 v[112:115], v[112:113], off offset:384

;     ...
;       if (kt + 1 < KT) {
;         unsigned char* base = smem + (par ^ 1) * BUFB;
; #pragma unroll
;         for (int i = 0; i < 4; ++i) *(u32x4*)(base + (srow + 64 * i) * LR + skc * 16) = ra[par ^ 1][i];
; #pragma unroll
;         for (int i = 0; i < 2; ++i) *(u32x4*)(base + BM * LR + (srow + 64 * i) * LR + skc * 16) = rb[par ^ 1][i];
;       }
.LBB0_719:
	s_waitcnt vmcnt(6)
	ds_write_b128 v205, v[68:71]
	ds_write_b128 v205, v[72:75] offset:9216
	ds_write_b128 v205, v[76:79] offset:18432
	ds_write_b128 v205, v[80:83] offset:27648
	ds_write_b128 v205, v[84:87] offset:36864
	ds_write_b128 v205, v[88:91] offset:46080

;     ...
;       if (kt + 1 < KT) {
;         unsigned char* base = smem + (par ^ 1) * BUFB;
; #pragma unroll
;         for (int i = 0; i < 4; ++i) *(u32x4*)(base + (srow + 64 * i) * LR + skc * 16) = ra[par ^ 1][i];
; #pragma unroll
;         for (int i = 0; i < 2; ++i) *(u32x4*)(base + BM * LR + (srow + 64 * i) * LR + skc * 16) = rb[par ^ 1][i];
;       }
.Lop3_lad_tail:
	s_waitcnt vmcnt(5)
	ds_write_b128 v205, v[92:95] offset:55296
	s_waitcnt vmcnt(3)
	ds_write_b128 v205, v[96:99] offset:64512
	v_mfma_f32_16x16x32_bf16 v[124:127], v[172:175], v[148:151], v[160:163]
	s_waitcnt vmcnt(2)
	ds_write_b128 v207, v[100:103] offset:55296
	s_waitcnt vmcnt(1)
	ds_write_b128 v208, v[104:107] offset:55296
	ds_write_b128 v209, v[108:111]
	s_waitcnt vmcnt(0)
	ds_write_b128 v209, v[112:115] offset:9216
	s_branch .Lop3_lad_join

;     ...
;     for (int kt2 = 0; kt2 < KT; kt2 += 2) {
; #pragma unroll
;      for (int par = 0; par < 2; ++par) {
;       const int kt = kt2 + par;
;       if (kt + 2 < KT) {
; #pragma unroll
;         for (int i = 0; i < 4; ++i) ra[par][i] = *(const u32x4*)(ap + (size_t)(64 * i) * K + (kt + 2) * BK);
; #pragma unroll
;         for (int i = 0; i < 2; ++i) rb[par][i] = *(const u32x4*)(bp + (size_t)(64 * i) * K + (kt + 2) * BK);
;       }
;       const unsigned char* abase = smem + par * BUFB + (wm * 64 + l15) * LR + g * 16;
;       const unsigned char* bbase = smem + par * BUFB + BM * LR + (wn * 64 + l15) * LR + g * 16;
;       if (!skip_mma)
; #pragma unroll
;       for (int ks = 0; ks < 2; ++ks) {
;         bf16x8 af[4], bfr[2];
; #pragma unroll
;         for (int mf = 0; mf < 4; ++mf) af[mf] = *(const bf16x8*)(abase + mf * 16 * LR + ks * 64);
; #pragma unroll
;         for (int nh = 0; nh < 2; ++nh) {
; #pragma unroll
;           for (int n2 = 0; n2 < 2; ++n2) bfr[n2] = *(const bf16x8*)(bbase + (nh * 2 + n2) * 16 * LR + ks * 64);
; #pragma unroll
;           for (int mf = 0; mf < 4; ++mf)
; #pragma unroll
;             for (int n2 = 0; n2 < 2; ++n2)
;               acc[mf][nh * 2 + n2] = __builtin_amdgcn_mfma_f32_16x16x32_bf16(af[mf], bfr[n2], acc[mf][nh * 2 + n2], 0, 0, 0);
;         }
;       }
;       if (NH > 0) {
;         const int per = KT / NH;
;         if (((kt + 1) % per) == 0) {
;           const int h = (kt + 1) / per - 1;
; #pragma unroll
;           for (int mf = 0; mf < 4; ++mf)
; #pragma unroll
;             for (int r = 0; r < 4; ++r) {
;               float s = rstdS[(wm * 64 + mf * 16 + 4 * g + r) * NH + h];
; #pragma unroll
;               for (int nf = 0; nf < 4; ++nf) {
;                 accT[mf][nf][r] += s * acc[mf][nf][r];
;                 acc[mf][nf][r] = 0.f;
;               }
;             }
;         }
;       }
;       if (kt + 1 < KT) {
;         unsigned char* base = smem + (par ^ 1) * BUFB;
; #pragma unroll
;         for (int i = 0; i < 4; ++i) *(u32x4*)(base + (srow + 64 * i) * LR + skc * 16) = ra[par ^ 1][i];
; #pragma unroll
;         for (int i = 0; i < 2; ++i) *(u32x4*)(base + BM * LR + (srow + 64 * i) * LR + skc * 16) = rb[par ^ 1][i];
;       }
;       __syncthreads();
;      }
.LBB0_2020:
	ds_read_b128 v[214:217], v212
	ds_read_b128 v[218:221], v206 offset:36864
	ds_read_b128 v[230:233], v212 offset:4608
	ds_read_b128 v[222:225], v206 offset:39168
	ds_read_b128 v[226:229], v212 offset:2304
	s_andn2_b64 vcc, exec, s[18:19]
	s_waitcnt lgkmcnt(3)
	v_mfma_f32_16x16x32_bf16 v[168:171], v[214:217], v[218:221], v[168:171]
	ds_read_b128 v[246:249], v212 offset:4672
	s_waitcnt lgkmcnt(2)
	v_mfma_f32_16x16x32_bf16 v[234:237], v[230:233], v[222:225], v[132:135]
	s_nop 2
	ds_read_b128 v[132:135], v212 offset:6912
	v_mfma_f32_16x16x32_bf16 v[164:167], v[214:217], v[222:225], v[164:167]
	s_waitcnt lgkmcnt(2)
	v_mfma_f32_16x16x32_bf16 v[156:159], v[226:229], v[218:221], v[156:159]
	v_mfma_f32_16x16x32_bf16 v[148:151], v[226:229], v[222:225], v[148:151]
	v_mfma_f32_16x16x32_bf16 v[140:143], v[230:233], v[218:221], v[140:143]
	s_waitcnt lgkmcnt(0)
	v_mfma_f32_16x16x32_bf16 v[218:221], v[132:135], v[218:221], v[124:127]
	v_mfma_f32_16x16x32_bf16 v[222:225], v[132:135], v[222:225], v[120:123]
	s_nop 1
	ds_read_b128 v[124:127], v206 offset:43776
	ds_read_b128 v[120:123], v206 offset:41472
	s_waitcnt lgkmcnt(0)
	v_mfma_f32_16x16x32_bf16 v[176:179], v[214:217], v[120:123], v[176:179]
	v_mfma_f32_16x16x32_bf16 v[172:175], v[214:217], v[124:127], v[172:175]
	v_mfma_f32_16x16x32_bf16 v[214:217], v[226:229], v[124:127], v[152:155]
	s_nop 2
	ds_read_b128 v[152:155], v212 offset:64
	v_mfma_f32_16x16x32_bf16 v[160:163], v[226:229], v[120:123], v[160:163]
	v_mfma_f32_16x16x32_bf16 v[226:229], v[230:233], v[120:123], v[144:147]
	s_nop 2
	ds_read_b128 v[144:147], v206 offset:36928
	v_mfma_f32_16x16x32_bf16 v[242:245], v[132:135], v[124:127], v[116:119]
	s_waitcnt lgkmcnt(0)
	v_mfma_f32_16x16x32_bf16 v[116:119], v[152:155], v[144:147], v[168:171]
	s_nop 2
	ds_read_b128 v[168:171], v206 offset:39232
	v_mfma_f32_16x16x32_bf16 v[230:233], v[230:233], v[124:127], v[136:139]
	v_mfma_f32_16x16x32_bf16 v[238:241], v[132:135], v[120:123], v[128:131]
	s_waitcnt lgkmcnt(0)
	v_mfma_f32_16x16x32_bf16 v[120:123], v[152:155], v[168:171], v[164:167]
	s_nop 2
	ds_read_b128 v[164:167], v212 offset:2368
	v_mfma_f32_16x16x32_bf16 v[136:139], v[246:249], v[168:171], v[234:237]
	s_nop 2
	ds_read_b128 v[234:237], v212 offset:6976
	s_waitcnt lgkmcnt(1)
	v_mfma_f32_16x16x32_bf16 v[124:127], v[164:167], v[144:147], v[156:159]
	v_mfma_f32_16x16x32_bf16 v[132:135], v[246:249], v[144:147], v[140:143]
	s_waitcnt lgkmcnt(0)
	v_mfma_f32_16x16x32_bf16 v[140:143], v[234:237], v[144:147], v[218:221]
	v_mfma_f32_16x16x32_bf16 v[144:147], v[234:237], v[168:171], v[222:225]
	s_nop 1
	ds_read_b128 v[218:221], v206 offset:41536
	ds_read_b128 v[222:225], v206 offset:43840
	v_mfma_f32_16x16x32_bf16 v[128:131], v[164:167], v[168:171], v[148:151]
	s_cbranch_vccnz .Lop8_lad_tail
	s_waitcnt vmcnt(11)
	ds_write_b128 v205, v[92:95] offset:55296
	s_waitcnt vmcnt(9)
	ds_write_b128 v205, v[96:99] offset:64512
	s_waitcnt vmcnt(8)
	ds_write_b128 v207, v[100:103] offset:55296
	s_waitcnt vmcnt(7)
	ds_write_b128 v208, v[104:107] offset:55296
	ds_write_b128 v209, v[108:111]
	s_waitcnt vmcnt(6)
	ds_write_b128 v209, v[112:115] offset:9216
.Lop8_lad_join:
	s_waitcnt lgkmcnt(7)
	v_mfma_f32_16x16x32_bf16 v[148:151], v[152:155], v[218:221], v[176:179]
	s_waitcnt lgkmcnt(0)
	s_barrier
	v_mfma_f32_16x16x32_bf16 v[152:155], v[152:155], v[222:225], v[172:175]
	v_mfma_f32_16x16x32_bf16 v[156:159], v[164:167], v[218:221], v[160:163]
	v_mfma_f32_16x16x32_bf16 v[160:163], v[164:167], v[222:225], v[214:217]
	v_mfma_f32_16x16x32_bf16 v[168:171], v[246:249], v[218:221], v[226:229]
	v_mfma_f32_16x16x32_bf16 v[172:175], v[246:249], v[222:225], v[230:233]
	v_mfma_f32_16x16x32_bf16 v[176:179], v[234:237], v[218:221], v[238:241]
	v_mfma_f32_16x16x32_bf16 v[164:167], v[234:237], v[222:225], v[242:245]
	s_cbranch_vccnz .LBB0_2022
	v_add_co_u32_e32 v92, vcc, 0x11262000, v192
	s_nop 1
	v_addc_co_u32_e32 v93, vcc, 0, v193, vcc
	v_add_co_u32_e32 v96, vcc, 0x112a2000, v192
	s_nop 1
	v_addc_co_u32_e32 v97, vcc, 0, v193, vcc
	v_add_co_u32_e32 v100, vcc, 0x112e2000, v192
	global_load_dwordx4 v[92:95], v[92:93], off offset:384
	s_nop 0
	global_load_dwordx4 v[96:99], v[96:97], off offset:384
	v_addc_co_u32_e32 v101, vcc, 0, v193, vcc
	v_add_co_u32_e32 v104, vcc, 0x11322000, v192
	s_nop 1
	v_addc_co_u32_e32 v105, vcc, 0, v193, vcc
	v_add_co_u32_e32 v108, vcc, 0x1c40000, v190
	global_load_dwordx4 v[100:103], v[100:101], off offset:384
	s_nop 0
	global_load_dwordx4 v[104:107], v[104:105], off offset:384
	v_addc_co_u32_e32 v109, vcc, 0, v191, vcc
	v_add_co_u32_e32 v112, vcc, 0x1c80000, v190
	s_nop 1
	v_addc_co_u32_e32 v113, vcc, 0, v191, vcc
	global_load_dwordx4 v[108:111], v[108:109], off offset:384
	s_nop 0
	global_load_dwordx4 v[112:115], v[112:113], off offset:384

;     ...
;       if (kt + 1 < KT) {
;         unsigned char* base = smem + (par ^ 1) * BUFB;
; #pragma unroll
;         for (int i = 0; i < 4; ++i) *(u32x4*)(base + (srow + 64 * i) * LR + skc * 16) = ra[par ^ 1][i];
; #pragma unroll
;         for (int i = 0; i < 2; ++i) *(u32x4*)(base + BM * LR + (srow + 64 * i) * LR + skc * 16) = rb[par ^ 1][i];
;       }
.LBB0_2024:
	s_add_i32 s18, s30, 3
	s_cmp_gt_u32 s18, 30
	s_cbranch_scc1 .LBB0_2026
	s_waitcnt vmcnt(6)
	ds_write_b128 v205, v[68:71]
	ds_write_b128 v205, v[72:75] offset:9216
	ds_write_b128 v205, v[76:79] offset:18432
	ds_write_b128 v205, v[80:83] offset:27648
	ds_write_b128 v205, v[84:87] offset:36864
	ds_write_b128 v205, v[88:91] offset:46080

;     ...
;       if (kt + 1 < KT) {
;         unsigned char* base = smem + (par ^ 1) * BUFB;
; #pragma unroll
;         for (int i = 0; i < 4; ++i) *(u32x4*)(base + (srow + 64 * i) * LR + skc * 16) = ra[par ^ 1][i];
; #pragma unroll
;         for (int i = 0; i < 2; ++i) *(u32x4*)(base + BM * LR + (srow + 64 * i) * LR + skc * 16) = rb[par ^ 1][i];
;       }
.Lop8_lad_tail:
	s_waitcnt vmcnt(5)
	ds_write_b128 v205, v[92:95] offset:55296
	s_waitcnt vmcnt(3)
	ds_write_b128 v205, v[96:99] offset:64512
	s_waitcnt vmcnt(2)
	ds_write_b128 v207, v[100:103] offset:55296
	s_waitcnt vmcnt(1)
	ds_write_b128 v208, v[104:107] offset:55296
	ds_write_b128 v209, v[108:111]
	s_waitcnt vmcnt(0)
	ds_write_b128 v209, v[112:115] offset:9216
	s_branch .Lop8_lad_join
